# non-temporal hint on the gate/up epilogue's H stores (written once, read in the next phase)
# baseline (speedup 1.0000x reference)
.LBB0_693:
	s_or_b64 exec, exec, s[18:19]
	v_lshl_add_u32 v136, s33, 10, v150
	ds_read2_b32 v[142:143], v136 offset1:16
	ds_read2_b32 v[140:141], v136 offset0:32 offset1:48
	ds_read2_b32 v[138:139], v136 offset0:128 offset1:144
	ds_read2_b32 v[136:137], v136 offset0:160 offset1:176
	v_readlane_b32 s16, v254, 1
	s_waitcnt lgkmcnt(0)
	v_pk_mul_f32 v[126:127], v[126:127], v[142:143] op_sel_hi:[1,0]
	v_pk_mul_f32 v[128:129], v[128:129], v[142:143] op_sel_hi:[1,0]
	v_pk_mul_f32 v[120:121], v[120:121], v[142:143] op_sel_hi:[1,0]
	v_pk_mul_f32 v[118:119], v[118:119], v[142:143] op_sel_hi:[1,0]
	v_pk_mul_f32 v[124:125], v[124:125], v[142:143] op_sel_hi:[1,0]
	v_pk_mul_f32 v[122:123], v[122:123], v[142:143] op_sel_hi:[1,0]
	v_pk_mul_f32 v[116:117], v[116:117], v[142:143] op_sel_hi:[1,0]
	v_pk_mul_f32 v[114:115], v[114:115], v[142:143] op_sel_hi:[1,0]
	v_mul_f32_e32 v142, 0xbfb8aa3b, v126
	v_exp_f32_e32 v142, v142
	v_lshl_or_b32 v144, s38, 7, v151
	v_readlane_b32 s17, v254, 2
	v_lshl_add_u32 v154, s37, 8, v147
	v_add_f32_e32 v142, 1.0, v142
	v_rcp_f32_e32 v142, v142
	v_ashrrev_i32_e32 v145, 31, v144
	s_movk_i32 s18, 0x1600
	v_pk_mul_f32 v[94:95], v[94:95], v[140:141] op_sel_hi:[1,0]
	v_mul_f32_e32 v126, v126, v142
	v_mul_f32_e32 v118, v118, v126
	v_mul_f32_e32 v126, 0xbfb8aa3b, v127
	v_exp_f32_e32 v126, v126
	v_pk_mul_f32 v[86:87], v[86:87], v[140:141] op_sel_hi:[1,0]
	v_pk_mul_f32 v[96:97], v[96:97], v[140:141] op_sel_hi:[1,0]
	v_pk_mul_f32 v[88:89], v[88:89], v[140:141] op_sel_hi:[1,0]
	v_add_f32_e32 v126, 1.0, v126
	v_rcp_f32_e32 v126, v126
	v_pk_mul_f32 v[90:91], v[90:91], v[140:141] op_sel_hi:[1,0]
	v_pk_mul_f32 v[92:93], v[92:93], v[140:141] op_sel_hi:[1,0]
	v_pk_mul_f32 v[62:63], v[62:63], v[138:139] op_sel_hi:[1,0]
	v_mul_f32_e32 v126, v127, v126
	v_mul_f32_e32 v119, v119, v126
	v_cvt_pk_bf16_f32 v118, v118, v119
	v_mul_f32_e32 v119, 0xbfb8aa3b, v128
	v_exp_f32_e32 v119, v119
	v_pk_mul_f32 v[54:55], v[54:55], v[138:139] op_sel_hi:[1,0]
	v_pk_mul_f32 v[64:65], v[64:65], v[138:139] op_sel_hi:[1,0]
	v_pk_mul_f32 v[56:57], v[56:57], v[138:139] op_sel_hi:[1,0]
	v_add_f32_e32 v119, 1.0, v119
	v_rcp_f32_e32 v119, v119
	v_pk_mul_f32 v[58:59], v[58:59], v[138:139] op_sel_hi:[1,0]
	v_pk_mul_f32 v[60:61], v[60:61], v[138:139] op_sel_hi:[1,0]
	v_pk_mul_f32 v[30:31], v[30:31], v[136:137] op_sel_hi:[1,0]
	v_mul_f32_e32 v119, v128, v119
	v_mul_f32_e32 v119, v120, v119
	v_mul_f32_e32 v120, 0xbfb8aa3b, v129
	v_exp_f32_e32 v120, v120
	v_pk_mul_f32 v[22:23], v[22:23], v[136:137] op_sel_hi:[1,0]
	v_pk_mul_f32 v[32:33], v[32:33], v[136:137] op_sel_hi:[1,0]
	v_pk_mul_f32 v[24:25], v[24:25], v[136:137] op_sel_hi:[1,0]
	v_add_f32_e32 v120, 1.0, v120
	v_rcp_f32_e32 v120, v120
	v_pk_mul_f32 v[26:27], v[26:27], v[136:137] op_sel_hi:[1,0]
	v_pk_mul_f32 v[28:29], v[28:29], v[136:137] op_sel_hi:[1,0]
	v_mul_f32_e32 v120, v129, v120
	v_mul_f32_e32 v120, v121, v120
	v_cvt_pk_bf16_f32 v119, v119, v120
	v_mul_f32_e32 v120, 0xbfb8aa3b, v122
	v_exp_f32_e32 v120, v120
	s_nop 0
	v_add_f32_e32 v120, 1.0, v120
	v_rcp_f32_e32 v120, v120
	s_nop 0
	v_mul_f32_e32 v120, v122, v120
	v_mul_f32_e32 v114, v114, v120
	v_mul_f32_e32 v120, 0xbfb8aa3b, v123
	v_exp_f32_e32 v120, v120
	s_nop 0
	v_add_f32_e32 v120, 1.0, v120
	v_rcp_f32_e32 v120, v120
	s_nop 0
	v_mul_f32_e32 v120, v123, v120
	v_mul_f32_e32 v115, v115, v120
	v_cvt_pk_bf16_f32 v120, v114, v115
	v_mul_f32_e32 v114, 0xbfb8aa3b, v124
	v_mul_f32_e32 v115, 0xbfb8aa3b, v125
	v_exp_f32_e32 v114, v114
	v_exp_f32_e32 v115, v115
	v_add_f32_e32 v114, 1.0, v114
	v_add_f32_e32 v115, 1.0, v115
	v_rcp_f32_e32 v114, v114
	v_rcp_f32_e32 v115, v115
	v_mul_f32_e32 v114, v124, v114
	v_mul_f32_e32 v115, v125, v115
	v_mul_f32_e32 v114, v116, v114
	v_mul_f32_e32 v115, v117, v115
	v_cvt_pk_bf16_f32 v121, v114, v115
	v_mov_b64_e32 v[114:115], s[16:17]
	v_mad_i64_i32 v[122:123], s[16:17], v154, s18, v[114:115]
	v_lshlrev_b64 v[116:117], 1, v[144:145]
	v_lshl_add_u64 v[122:123], v[122:123], 0, v[116:117]
	global_store_dwordx4 v[122:123], v[118:121], off nt
	s_nop 1
	v_or_b32_e32 v119, 16, v154
	v_mov_b32_e32 v118, v143
	v_pk_mul_f32 v[110:111], v[110:111], v[118:119] op_sel_hi:[1,0]
	v_pk_mul_f32 v[120:121], v[100:101], v[118:119] op_sel_hi:[1,0]
	v_pk_mul_f32 v[100:101], v[98:99], v[118:119] op_sel_hi:[1,0]
	v_mul_f32_e32 v98, 0xbfb8aa3b, v110
	v_mul_f32_e32 v99, 0xbfb8aa3b, v111
	v_exp_f32_e32 v98, v98
	v_exp_f32_e32 v99, v99
	v_pk_mul_f32 v[102:103], v[102:103], v[118:119] op_sel_hi:[1,0]
	v_pk_mul_f32 v[112:113], v[112:113], v[118:119] op_sel_hi:[1,0]
	v_add_f32_e32 v98, 1.0, v98
	v_add_f32_e32 v99, 1.0, v99
	v_rcp_f32_e32 v98, v98
	v_rcp_f32_e32 v99, v99
	v_pk_mul_f32 v[104:105], v[104:105], v[118:119] op_sel_hi:[1,0]
	v_pk_mul_f32 v[106:107], v[106:107], v[118:119] op_sel_hi:[1,0]
	v_mul_f32_e32 v98, v110, v98
	v_mul_f32_e32 v99, v111, v99
	v_mul_f32_e32 v98, v102, v98
	v_mul_f32_e32 v99, v103, v99
	v_cvt_pk_bf16_f32 v98, v98, v99
	v_mul_f32_e32 v99, 0xbfb8aa3b, v112
	v_mul_f32_e32 v102, 0xbfb8aa3b, v113
	v_exp_f32_e32 v99, v99
	v_exp_f32_e32 v102, v102
	v_pk_mul_f32 v[108:109], v[108:109], v[118:119] op_sel_hi:[1,0]
	v_add_f32_e32 v99, 1.0, v99
	v_add_f32_e32 v102, 1.0, v102
	v_rcp_f32_e32 v99, v99
	v_rcp_f32_e32 v102, v102
	v_mul_f32_e32 v99, v112, v99
	v_mul_f32_e32 v102, v113, v102
	v_mul_f32_e32 v99, v104, v99
	v_mul_f32_e32 v102, v105, v102
	v_cvt_pk_bf16_f32 v99, v99, v102
	v_mul_f32_e32 v102, 0xbfb8aa3b, v106
	v_exp_f32_e32 v102, v102
	s_nop 0
	v_add_f32_e32 v102, 1.0, v102
	v_rcp_f32_e32 v102, v102
	s_nop 0
	v_mul_f32_e32 v102, v106, v102
	v_mul_f32_e32 v100, v100, v102
	v_mul_f32_e32 v102, 0xbfb8aa3b, v107
	v_exp_f32_e32 v102, v102
	s_nop 0
	v_add_f32_e32 v102, 1.0, v102
	v_rcp_f32_e32 v102, v102
	s_nop 0
	v_mul_f32_e32 v102, v107, v102
	v_mul_f32_e32 v101, v101, v102
	v_cvt_pk_bf16_f32 v100, v100, v101
	v_mul_f32_e32 v101, 0xbfb8aa3b, v108
	v_mul_f32_e32 v102, 0xbfb8aa3b, v109
	v_exp_f32_e32 v101, v101
	v_exp_f32_e32 v102, v102
	v_add_f32_e32 v101, 1.0, v101
	v_add_f32_e32 v102, 1.0, v102
	v_rcp_f32_e32 v101, v101
	v_rcp_f32_e32 v102, v102
	v_mul_f32_e32 v101, v108, v101
	v_mul_f32_e32 v102, v109, v102
	v_mul_f32_e32 v101, v120, v101
	v_mul_f32_e32 v102, v121, v102
	v_cvt_pk_bf16_f32 v101, v101, v102
	v_mad_i64_i32 v[102:103], s[16:17], v119, s18, v[114:115]
	v_lshl_add_u64 v[102:103], v[102:103], 0, v[116:117]
	global_store_dwordx4 v[102:103], v[98:101], off nt
	s_nop 1
	v_pk_mul_f32 v[98:99], v[84:85], v[140:141] op_sel_hi:[1,0]
	v_pk_mul_f32 v[84:85], v[82:83], v[140:141] op_sel_hi:[1,0]
	v_mul_f32_e32 v82, 0xbfb8aa3b, v94
	v_mul_f32_e32 v83, 0xbfb8aa3b, v95
	v_exp_f32_e32 v82, v82
	v_exp_f32_e32 v83, v83
	v_or_b32_e32 v100, 32, v154
	v_add_f32_e32 v82, 1.0, v82
	v_add_f32_e32 v83, 1.0, v83
	v_rcp_f32_e32 v82, v82
	v_rcp_f32_e32 v83, v83
	v_mul_f32_e32 v82, v94, v82
	v_mul_f32_e32 v83, v95, v83
	v_mul_f32_e32 v82, v86, v82
	v_mul_f32_e32 v83, v87, v83
	v_cvt_pk_bf16_f32 v82, v82, v83
	v_mul_f32_e32 v83, 0xbfb8aa3b, v96
	v_mul_f32_e32 v86, 0xbfb8aa3b, v97
	v_exp_f32_e32 v83, v83
	v_exp_f32_e32 v86, v86
	v_add_f32_e32 v83, 1.0, v83
	v_add_f32_e32 v86, 1.0, v86
	v_rcp_f32_e32 v83, v83
	v_rcp_f32_e32 v86, v86
	v_mul_f32_e32 v83, v96, v83
	v_mul_f32_e32 v86, v97, v86
	v_mul_f32_e32 v83, v88, v83
	v_mul_f32_e32 v86, v89, v86
	v_cvt_pk_bf16_f32 v83, v83, v86
	v_mul_f32_e32 v86, 0xbfb8aa3b, v90
	v_exp_f32_e32 v86, v86
	s_nop 0
	v_add_f32_e32 v86, 1.0, v86
	v_rcp_f32_e32 v86, v86
	s_nop 0
	v_mul_f32_e32 v86, v90, v86
	v_mul_f32_e32 v84, v84, v86
	v_mul_f32_e32 v86, 0xbfb8aa3b, v91
	v_exp_f32_e32 v86, v86
	s_nop 0
	v_add_f32_e32 v86, 1.0, v86
	v_rcp_f32_e32 v86, v86
	s_nop 0
	v_mul_f32_e32 v86, v91, v86
	v_mul_f32_e32 v85, v85, v86
	v_cvt_pk_bf16_f32 v84, v84, v85
	v_mul_f32_e32 v85, 0xbfb8aa3b, v92
	v_mul_f32_e32 v86, 0xbfb8aa3b, v93
	v_exp_f32_e32 v85, v85
	v_exp_f32_e32 v86, v86
	v_add_f32_e32 v85, 1.0, v85
	v_add_f32_e32 v86, 1.0, v86
	v_rcp_f32_e32 v85, v85
	v_rcp_f32_e32 v86, v86
	v_mul_f32_e32 v85, v92, v85
	v_mul_f32_e32 v86, v93, v86
	v_mul_f32_e32 v85, v98, v85
	v_mul_f32_e32 v86, v99, v86
	v_cvt_pk_bf16_f32 v85, v85, v86
	v_mad_i64_i32 v[86:87], s[16:17], v100, s18, v[114:115]
	v_lshl_add_u64 v[86:87], v[86:87], 0, v[116:117]
	global_store_dwordx4 v[86:87], v[82:85], off nt
	s_nop 1
	v_or_b32_e32 v83, 48, v154
	v_mov_b32_e32 v82, v141
	v_pk_mul_f32 v[78:79], v[78:79], v[82:83] op_sel_hi:[1,0]
	v_pk_mul_f32 v[84:85], v[68:69], v[82:83] op_sel_hi:[1,0]
	v_pk_mul_f32 v[68:69], v[66:67], v[82:83] op_sel_hi:[1,0]
	v_mul_f32_e32 v66, 0xbfb8aa3b, v78
	v_mul_f32_e32 v67, 0xbfb8aa3b, v79
	v_exp_f32_e32 v66, v66
	v_exp_f32_e32 v67, v67
	v_pk_mul_f32 v[70:71], v[70:71], v[82:83] op_sel_hi:[1,0]
	v_pk_mul_f32 v[80:81], v[80:81], v[82:83] op_sel_hi:[1,0]
	v_add_f32_e32 v66, 1.0, v66
	v_add_f32_e32 v67, 1.0, v67
	v_rcp_f32_e32 v66, v66
	v_rcp_f32_e32 v67, v67
	v_pk_mul_f32 v[72:73], v[72:73], v[82:83] op_sel_hi:[1,0]
	v_pk_mul_f32 v[74:75], v[74:75], v[82:83] op_sel_hi:[1,0]
	v_mul_f32_e32 v66, v78, v66
	v_mul_f32_e32 v67, v79, v67
	v_mul_f32_e32 v66, v70, v66
	v_mul_f32_e32 v67, v71, v67
	v_cvt_pk_bf16_f32 v66, v66, v67
	v_mul_f32_e32 v67, 0xbfb8aa3b, v80
	v_mul_f32_e32 v70, 0xbfb8aa3b, v81
	v_exp_f32_e32 v67, v67
	v_exp_f32_e32 v70, v70
	v_pk_mul_f32 v[76:77], v[76:77], v[82:83] op_sel_hi:[1,0]
	v_add_f32_e32 v67, 1.0, v67
	v_add_f32_e32 v70, 1.0, v70
	v_rcp_f32_e32 v67, v67
	v_rcp_f32_e32 v70, v70
	v_mul_f32_e32 v67, v80, v67
	v_mul_f32_e32 v70, v81, v70
	v_mul_f32_e32 v67, v72, v67
	v_mul_f32_e32 v70, v73, v70
	v_cvt_pk_bf16_f32 v67, v67, v70
	v_mul_f32_e32 v70, 0xbfb8aa3b, v74
	v_exp_f32_e32 v70, v70
	s_nop 0
	v_add_f32_e32 v70, 1.0, v70
	v_rcp_f32_e32 v70, v70
	s_nop 0
	v_mul_f32_e32 v70, v74, v70
	v_mul_f32_e32 v68, v68, v70
	v_mul_f32_e32 v70, 0xbfb8aa3b, v75
	v_exp_f32_e32 v70, v70
	s_nop 0
	v_add_f32_e32 v70, 1.0, v70
	v_rcp_f32_e32 v70, v70
	s_nop 0
	v_mul_f32_e32 v70, v75, v70
	v_mul_f32_e32 v69, v69, v70
	v_cvt_pk_bf16_f32 v68, v68, v69
	v_mul_f32_e32 v69, 0xbfb8aa3b, v76
	v_mul_f32_e32 v70, 0xbfb8aa3b, v77
	v_exp_f32_e32 v69, v69
	v_exp_f32_e32 v70, v70
	v_add_f32_e32 v69, 1.0, v69
	v_add_f32_e32 v70, 1.0, v70
	v_rcp_f32_e32 v69, v69
	v_rcp_f32_e32 v70, v70
	v_mul_f32_e32 v69, v76, v69
	v_mul_f32_e32 v70, v77, v70
	v_mul_f32_e32 v69, v84, v69
	v_mul_f32_e32 v70, v85, v70
	v_cvt_pk_bf16_f32 v69, v69, v70
	v_mad_i64_i32 v[70:71], s[16:17], v83, s18, v[114:115]
	v_lshl_add_u64 v[70:71], v[70:71], 0, v[116:117]
	global_store_dwordx4 v[70:71], v[66:69], off nt
	s_nop 1
	v_pk_mul_f32 v[66:67], v[52:53], v[138:139] op_sel_hi:[1,0]
	v_pk_mul_f32 v[52:53], v[50:51], v[138:139] op_sel_hi:[1,0]
	v_mul_f32_e32 v50, 0xbfb8aa3b, v62
	v_mul_f32_e32 v51, 0xbfb8aa3b, v63
	v_exp_f32_e32 v50, v50
	v_exp_f32_e32 v51, v51
	v_add_u32_e32 v68, 0x80, v154
	v_add_f32_e32 v50, 1.0, v50
	v_add_f32_e32 v51, 1.0, v51
	v_rcp_f32_e32 v50, v50
	v_rcp_f32_e32 v51, v51
	v_mul_f32_e32 v50, v62, v50
	v_mul_f32_e32 v51, v63, v51
	v_mul_f32_e32 v50, v54, v50
	v_mul_f32_e32 v51, v55, v51
	v_cvt_pk_bf16_f32 v50, v50, v51
	v_mul_f32_e32 v51, 0xbfb8aa3b, v64
	v_mul_f32_e32 v54, 0xbfb8aa3b, v65
	v_exp_f32_e32 v51, v51
	v_exp_f32_e32 v54, v54
	v_add_f32_e32 v51, 1.0, v51
	v_add_f32_e32 v54, 1.0, v54
	v_rcp_f32_e32 v51, v51
	v_rcp_f32_e32 v54, v54
	v_mul_f32_e32 v51, v64, v51
	v_mul_f32_e32 v54, v65, v54
	v_mul_f32_e32 v51, v56, v51
	v_mul_f32_e32 v54, v57, v54
	v_cvt_pk_bf16_f32 v51, v51, v54
	v_mul_f32_e32 v54, 0xbfb8aa3b, v58
	v_exp_f32_e32 v54, v54
	s_nop 0
	v_add_f32_e32 v54, 1.0, v54
	v_rcp_f32_e32 v54, v54
	s_nop 0
	v_mul_f32_e32 v54, v58, v54
	v_mul_f32_e32 v52, v52, v54
	v_mul_f32_e32 v54, 0xbfb8aa3b, v59
	v_exp_f32_e32 v54, v54
	s_nop 0
	v_add_f32_e32 v54, 1.0, v54
	v_rcp_f32_e32 v54, v54
	s_nop 0
	v_mul_f32_e32 v54, v59, v54
	v_mul_f32_e32 v53, v53, v54
	v_cvt_pk_bf16_f32 v52, v52, v53
	v_mul_f32_e32 v53, 0xbfb8aa3b, v60
	v_mul_f32_e32 v54, 0xbfb8aa3b, v61
	v_exp_f32_e32 v53, v53
	v_exp_f32_e32 v54, v54
	v_add_f32_e32 v53, 1.0, v53
	v_add_f32_e32 v54, 1.0, v54
	v_rcp_f32_e32 v53, v53
	v_rcp_f32_e32 v54, v54
	v_mul_f32_e32 v53, v60, v53
	v_mul_f32_e32 v54, v61, v54
	v_mul_f32_e32 v53, v66, v53
	v_mul_f32_e32 v54, v67, v54
	v_cvt_pk_bf16_f32 v53, v53, v54
	v_mad_i64_i32 v[54:55], s[16:17], v68, s18, v[114:115]
	v_lshl_add_u64 v[54:55], v[54:55], 0, v[116:117]
	global_store_dwordx4 v[54:55], v[50:53], off nt
	s_nop 1
	v_add_u32_e32 v51, 0x90, v154
	v_mov_b32_e32 v50, v139
	v_pk_mul_f32 v[46:47], v[46:47], v[50:51] op_sel_hi:[1,0]
	v_pk_mul_f32 v[52:53], v[36:37], v[50:51] op_sel_hi:[1,0]
	v_pk_mul_f32 v[36:37], v[34:35], v[50:51] op_sel_hi:[1,0]
	v_mul_f32_e32 v34, 0xbfb8aa3b, v46
	v_mul_f32_e32 v35, 0xbfb8aa3b, v47
	v_exp_f32_e32 v34, v34
	v_exp_f32_e32 v35, v35
	v_pk_mul_f32 v[38:39], v[38:39], v[50:51] op_sel_hi:[1,0]
	v_pk_mul_f32 v[48:49], v[48:49], v[50:51] op_sel_hi:[1,0]
	v_add_f32_e32 v34, 1.0, v34
	v_add_f32_e32 v35, 1.0, v35
	v_rcp_f32_e32 v34, v34
	v_rcp_f32_e32 v35, v35
	v_pk_mul_f32 v[40:41], v[40:41], v[50:51] op_sel_hi:[1,0]
	v_pk_mul_f32 v[42:43], v[42:43], v[50:51] op_sel_hi:[1,0]
	v_mul_f32_e32 v34, v46, v34
	v_mul_f32_e32 v35, v47, v35
	v_mul_f32_e32 v34, v38, v34
	v_mul_f32_e32 v35, v39, v35
	v_cvt_pk_bf16_f32 v34, v34, v35
	v_mul_f32_e32 v35, 0xbfb8aa3b, v48
	v_mul_f32_e32 v38, 0xbfb8aa3b, v49
	v_exp_f32_e32 v35, v35
	v_exp_f32_e32 v38, v38
	v_pk_mul_f32 v[44:45], v[44:45], v[50:51] op_sel_hi:[1,0]
	v_add_f32_e32 v35, 1.0, v35
	v_add_f32_e32 v38, 1.0, v38
	v_rcp_f32_e32 v35, v35
	v_rcp_f32_e32 v38, v38
	v_mul_f32_e32 v35, v48, v35
	v_mul_f32_e32 v38, v49, v38
	v_mul_f32_e32 v35, v40, v35
	v_mul_f32_e32 v38, v41, v38
	v_cvt_pk_bf16_f32 v35, v35, v38
	v_mul_f32_e32 v38, 0xbfb8aa3b, v42
	v_exp_f32_e32 v38, v38
	s_nop 0
	v_add_f32_e32 v38, 1.0, v38
	v_rcp_f32_e32 v38, v38
	s_nop 0
	v_mul_f32_e32 v38, v42, v38
	v_mul_f32_e32 v36, v36, v38
	v_mul_f32_e32 v38, 0xbfb8aa3b, v43
	v_exp_f32_e32 v38, v38
	s_nop 0
	v_add_f32_e32 v38, 1.0, v38
	v_rcp_f32_e32 v38, v38
	s_nop 0
	v_mul_f32_e32 v38, v43, v38
	v_mul_f32_e32 v37, v37, v38
	v_cvt_pk_bf16_f32 v36, v36, v37
	v_mul_f32_e32 v37, 0xbfb8aa3b, v44
	v_mul_f32_e32 v38, 0xbfb8aa3b, v45
	v_exp_f32_e32 v37, v37
	v_exp_f32_e32 v38, v38
	v_add_f32_e32 v37, 1.0, v37
	v_add_f32_e32 v38, 1.0, v38
	v_rcp_f32_e32 v37, v37
	v_rcp_f32_e32 v38, v38
	v_mul_f32_e32 v37, v44, v37
	v_mul_f32_e32 v38, v45, v38
	v_mul_f32_e32 v37, v52, v37
	v_mul_f32_e32 v38, v53, v38
	v_cvt_pk_bf16_f32 v37, v37, v38
	v_mad_i64_i32 v[38:39], s[16:17], v51, s18, v[114:115]
	v_lshl_add_u64 v[38:39], v[38:39], 0, v[116:117]
	global_store_dwordx4 v[38:39], v[34:37], off nt
	s_nop 1
	v_pk_mul_f32 v[34:35], v[20:21], v[136:137] op_sel_hi:[1,0]
	v_pk_mul_f32 v[20:21], v[18:19], v[136:137] op_sel_hi:[1,0]
	v_mul_f32_e32 v18, 0xbfb8aa3b, v30
	v_mul_f32_e32 v19, 0xbfb8aa3b, v31
	v_exp_f32_e32 v18, v18
	v_exp_f32_e32 v19, v19
	v_add_u32_e32 v36, 0xa0, v154
	v_add_f32_e32 v18, 1.0, v18
	v_add_f32_e32 v19, 1.0, v19
	v_rcp_f32_e32 v18, v18
	v_rcp_f32_e32 v19, v19
	v_mul_f32_e32 v18, v30, v18
	v_mul_f32_e32 v19, v31, v19
	v_mul_f32_e32 v18, v22, v18
	v_mul_f32_e32 v19, v23, v19
	v_cvt_pk_bf16_f32 v18, v18, v19
	v_mul_f32_e32 v19, 0xbfb8aa3b, v32
	v_mul_f32_e32 v22, 0xbfb8aa3b, v33
	v_exp_f32_e32 v19, v19
	v_exp_f32_e32 v22, v22
	v_add_f32_e32 v19, 1.0, v19
	v_add_f32_e32 v22, 1.0, v22
	v_rcp_f32_e32 v19, v19
	v_rcp_f32_e32 v22, v22
	v_mul_f32_e32 v19, v32, v19
	v_mul_f32_e32 v22, v33, v22
	v_mul_f32_e32 v19, v24, v19
	v_mul_f32_e32 v22, v25, v22
	v_cvt_pk_bf16_f32 v19, v19, v22
	v_mul_f32_e32 v22, 0xbfb8aa3b, v26
	v_exp_f32_e32 v22, v22
	s_nop 0
	v_add_f32_e32 v22, 1.0, v22
	v_rcp_f32_e32 v22, v22
	s_nop 0
	v_mul_f32_e32 v22, v26, v22
	v_mul_f32_e32 v20, v20, v22
	v_mul_f32_e32 v22, 0xbfb8aa3b, v27
	v_exp_f32_e32 v22, v22
	s_nop 0
	v_add_f32_e32 v22, 1.0, v22
	v_rcp_f32_e32 v22, v22
	s_nop 0
	v_mul_f32_e32 v22, v27, v22
	v_mul_f32_e32 v21, v21, v22
	v_cvt_pk_bf16_f32 v20, v20, v21
	v_mul_f32_e32 v21, 0xbfb8aa3b, v28
	v_mul_f32_e32 v22, 0xbfb8aa3b, v29
	v_exp_f32_e32 v21, v21
	v_exp_f32_e32 v22, v22
	v_add_f32_e32 v21, 1.0, v21
	v_add_f32_e32 v22, 1.0, v22
	v_rcp_f32_e32 v21, v21
	v_rcp_f32_e32 v22, v22
	v_mul_f32_e32 v21, v28, v21
	v_mul_f32_e32 v22, v29, v22
	v_mul_f32_e32 v21, v34, v21
	v_mul_f32_e32 v22, v35, v22
	v_cvt_pk_bf16_f32 v21, v21, v22
	v_mad_i64_i32 v[22:23], s[16:17], v36, s18, v[114:115]
	v_lshl_add_u64 v[22:23], v[22:23], 0, v[116:117]
	global_store_dwordx4 v[22:23], v[18:21], off nt
	s_nop 1
	v_add_u32_e32 v19, 0xb0, v154
	v_mov_b32_e32 v18, v137
	v_pk_mul_f32 v[14:15], v[14:15], v[18:19] op_sel_hi:[1,0]
	v_pk_mul_f32 v[20:21], v[4:5], v[18:19] op_sel_hi:[1,0]
	v_pk_mul_f32 v[4:5], v[2:3], v[18:19] op_sel_hi:[1,0]
	v_mul_f32_e32 v2, 0xbfb8aa3b, v14
	v_mul_f32_e32 v3, 0xbfb8aa3b, v15
	v_exp_f32_e32 v2, v2
	v_exp_f32_e32 v3, v3
	v_pk_mul_f32 v[6:7], v[6:7], v[18:19] op_sel_hi:[1,0]
	v_pk_mul_f32 v[16:17], v[16:17], v[18:19] op_sel_hi:[1,0]
	v_add_f32_e32 v2, 1.0, v2
	v_add_f32_e32 v3, 1.0, v3
	v_rcp_f32_e32 v2, v2
	v_rcp_f32_e32 v3, v3
	v_pk_mul_f32 v[8:9], v[8:9], v[18:19] op_sel_hi:[1,0]
	v_pk_mul_f32 v[10:11], v[10:11], v[18:19] op_sel_hi:[1,0]
	v_mul_f32_e32 v2, v14, v2
	v_mul_f32_e32 v3, v15, v3
	v_mul_f32_e32 v2, v6, v2
	v_mul_f32_e32 v3, v7, v3
	v_cvt_pk_bf16_f32 v2, v2, v3
	v_mul_f32_e32 v3, 0xbfb8aa3b, v16
	v_mul_f32_e32 v6, 0xbfb8aa3b, v17
	v_exp_f32_e32 v3, v3
	v_exp_f32_e32 v6, v6
	v_pk_mul_f32 v[12:13], v[12:13], v[18:19] op_sel_hi:[1,0]
	v_add_f32_e32 v3, 1.0, v3
	v_add_f32_e32 v6, 1.0, v6
	v_rcp_f32_e32 v3, v3
	v_rcp_f32_e32 v6, v6
	v_mul_f32_e32 v3, v16, v3
	v_mul_f32_e32 v6, v17, v6
	v_mul_f32_e32 v3, v8, v3
	v_mul_f32_e32 v6, v9, v6
	v_cvt_pk_bf16_f32 v3, v3, v6
	v_mul_f32_e32 v6, 0xbfb8aa3b, v10
	v_exp_f32_e32 v6, v6
	s_nop 0
	v_add_f32_e32 v6, 1.0, v6
	v_rcp_f32_e32 v6, v6
	s_nop 0
	v_mul_f32_e32 v6, v10, v6
	v_mul_f32_e32 v4, v4, v6
	v_mul_f32_e32 v6, 0xbfb8aa3b, v11
	v_exp_f32_e32 v6, v6
	s_nop 0
	v_add_f32_e32 v6, 1.0, v6
	v_rcp_f32_e32 v6, v6
	s_nop 0
	v_mul_f32_e32 v6, v11, v6
	v_mul_f32_e32 v5, v5, v6
	v_cvt_pk_bf16_f32 v4, v4, v5
	v_mul_f32_e32 v5, 0xbfb8aa3b, v12
	v_mul_f32_e32 v6, 0xbfb8aa3b, v13
	v_exp_f32_e32 v5, v5
	v_exp_f32_e32 v6, v6
	v_add_f32_e32 v5, 1.0, v5
	v_add_f32_e32 v6, 1.0, v6
	v_rcp_f32_e32 v5, v5
	v_rcp_f32_e32 v6, v6
	v_mul_f32_e32 v5, v12, v5
	v_mul_f32_e32 v6, v13, v6
	v_mul_f32_e32 v5, v20, v5
	v_mul_f32_e32 v6, v21, v6
	v_cvt_pk_bf16_f32 v5, v5, v6
	v_mad_i64_i32 v[6:7], s[16:17], v19, s18, v[114:115]
	v_lshl_add_u64 v[6:7], v[6:7], 0, v[116:117]
	global_store_dwordx4 v[6:7], v[2:5], off nt
	s_andn2_b64 vcc, exec, s[10:11]
	s_mov_b64 s[10:11], -1
	s_cbranch_vccnz .LBB0_684
	s_and_saveexec_b64 s[10:11], s[40:41]
	s_lshl_b32 s16, s33, 8
	s_xor_b32 s16, s16, 0x100
	v_lshl_add_u32 v2, s16, 2, v149
	ds_write_b32 v2, v153
	s_or_b64 exec, exec, s[10:11]
	s_andn2_b64 vcc, exec, s[4:5]
	s_cbranch_vccnz .LBB0_683
	s_barrier
	s_branch .LBB0_683
